# FoX attention: dword touch loads two K/V tiles ahead (L2 prefetch), half-step waits leave the 4 touches in flight; on top of snaked MFMA order
# baseline (speedup 1.0000x reference)
; template <int VB>
; __device__ __forceinline__ void pv_tile(f32x16* o, int vb0, bf16x8 pa0, bf16x8 pa1, bf16x8 pa2, bf16x8 pa3) {
;     ...
;     PV_D0(0); PV_D0(1); PV_D0(2); PV_D0(3);
.LBB0_1466:
	s_add_u32 s100, s82, 0x2570a000
	s_addc_u32 s101, s83, 0
	v_lshl_add_u64 v[254:255], v[188:189], 0, s[100:101]
	global_load_dword v253, v[254:255], off
	v_lshl_add_u64 v[254:255], v[190:191], 0, s[100:101]
	global_load_dword v253, v[254:255], off
	s_add_u32 s100, s82, 0x25708000
	s_addc_u32 s101, s83, 0
	v_lshl_add_u64 v[254:255], v[192:193], 0, s[100:101]
	global_load_dword v253, v[254:255], off
	v_lshl_add_u64 v[254:255], v[194:195], 0, s[100:101]
	global_load_dword v253, v[254:255], off
	ds_read_b64_tr_b16 v[130:131], v175 offset:0
	ds_read_b64_tr_b16 v[132:133], v175 offset:0x800
	ds_read_b64_tr_b16 v[134:135], v175 offset:0x1000
	ds_read_b64_tr_b16 v[136:137], v175 offset:0x1800
	ds_read_b64_tr_b16 v[138:139], v175 offset:0x2000
	ds_read_b64_tr_b16 v[140:141], v175 offset:0x2800
	ds_read_b64_tr_b16 v[142:143], v175 offset:0x3000
	ds_read_b64_tr_b16 v[144:145], v175 offset:0x3800
	s_waitcnt lgkmcnt(0)
	s_nop 0
	v_mfma_f32_32x32x16_bf16 v[66:81], v[82:85], v[130:133], v[66:81]
	ds_read_b64_tr_b16 v[130:131], v175 offset:0x200
	ds_read_b64_tr_b16 v[132:133], v175 offset:0xa00
	v_mfma_f32_32x32x16_bf16 v[66:81], v[118:121], v[134:137], v[66:81]
	ds_read_b64_tr_b16 v[134:135], v175 offset:0x1200
	ds_read_b64_tr_b16 v[136:137], v175 offset:0x1a00
	v_mfma_f32_32x32x16_bf16 v[66:81], v[122:125], v[138:141], v[66:81]
	ds_read_b64_tr_b16 v[138:139], v175 offset:0x2200
	ds_read_b64_tr_b16 v[140:141], v175 offset:0x2a00
	ds_read_b64_tr_b16 v[156:157], v175 offset:0x3200
	ds_read_b64_tr_b16 v[158:159], v175 offset:0x3a00
	s_waitcnt lgkmcnt(0)
	v_mfma_f32_32x32x16_bf16 v[66:81], v[126:129], v[142:145], v[66:81]
	v_mfma_f32_32x32x16_bf16 v[50:65], v[82:85], v[130:133], v[50:65]
	ds_read_b64_tr_b16 v[130:131], v175 offset:0x400
	ds_read_b64_tr_b16 v[132:133], v175 offset:0xc00
	v_mfma_f32_32x32x16_bf16 v[50:65], v[118:121], v[134:137], v[50:65]
	ds_read_b64_tr_b16 v[134:135], v175 offset:0x1400
	ds_read_b64_tr_b16 v[136:137], v175 offset:0x1c00
	v_mfma_f32_32x32x16_bf16 v[50:65], v[122:125], v[138:141], v[50:65]
	ds_read_b64_tr_b16 v[138:139], v175 offset:0x2400
	ds_read_b64_tr_b16 v[140:141], v175 offset:0x2c00
	ds_read_b64_tr_b16 v[142:143], v175 offset:0x3400
	ds_read_b64_tr_b16 v[144:145], v175 offset:0x3c00
	s_waitcnt lgkmcnt(0)
	v_mfma_f32_32x32x16_bf16 v[50:65], v[126:129], v[156:159], v[50:65]
	v_mfma_f32_32x32x16_bf16 v[34:49], v[82:85], v[130:133], v[34:49]
	ds_read_b64_tr_b16 v[130:131], v175 offset:0x600
	ds_read_b64_tr_b16 v[132:133], v175 offset:0xe00
	v_mfma_f32_32x32x16_bf16 v[34:49], v[118:121], v[134:137], v[34:49]
	ds_read_b64_tr_b16 v[134:135], v175 offset:0x1600
	ds_read_b64_tr_b16 v[136:137], v175 offset:0x1e00
	v_mfma_f32_32x32x16_bf16 v[34:49], v[122:125], v[138:141], v[34:49]
	ds_read_b64_tr_b16 v[138:139], v175 offset:0x2600
	ds_read_b64_tr_b16 v[140:141], v175 offset:0x2e00
	ds_read_b64_tr_b16 v[156:157], v175 offset:0x3600
	ds_read_b64_tr_b16 v[158:159], v175 offset:0x3e00
	s_waitcnt lgkmcnt(0)
	v_mfma_f32_32x32x16_bf16 v[34:49], v[126:129], v[142:145], v[34:49]
	v_mfma_f32_32x32x16_bf16 v[18:33], v[82:85], v[130:133], v[18:33]
	s_cmp_le_i32 s74, s73
	v_mfma_f32_32x32x16_bf16 v[18:33], v[118:121], v[134:137], v[18:33]
	v_mfma_f32_32x32x16_bf16 v[18:33], v[122:125], v[138:141], v[18:33]
	v_mfma_f32_32x32x16_bf16 v[18:33], v[126:129], v[156:159], v[18:33]
	s_cbranch_scc1 .LBB0_1468
; __device__ __forceinline__ void mask_tile(f32x16& p0, f32x16& p1, int dq) {
;     const float NEG = -__builtin_inff();
; #pragma unroll
;     for (int r = 0; r < 16; ++r) {
;         const int c = (r & 3) + 8 * (r >> 2);
;         if (dq - c < 0) p0[r] = NEG;
;         if (dq - c - 32 < 0) p1[r] = NEG;
;     }
; }
; __device__ __forceinline__ void partialSM(f32x16& p0, f32x16& p1, float& m_reg, float& mn, float& alpha) {
;     float pmax = p0[0];
; #pragma unroll
;     for (int r = 1; r < 16; ++r) pmax = fmaxf(pmax, p0[r]);
; #pragma unroll
;     for (int r = 0; r < 16; ++r) pmax = fmaxf(pmax, p1[r]);
;     { auto rr = __builtin_amdgcn_permlane32_swap(__float_as_uint(pmax), __float_as_uint(pmax), false, false);
;       pmax = fmaxf(__uint_as_float(rr[0]), __uint_as_float(rr[1])); }
;     if (__builtin_expect(__all((pmax - m_reg) * SCALE <= THR), 1)) { mn = m_reg; alpha = 1.f; }
;     else { mn = fmaxf(m_reg, pmax); alpha = __builtin_amdgcn_exp2f((m_reg - mn) * C2); m_reg = mn; }
	v_cmp_gt_i32_e64 s[68:69], 26, v230
	v_cmp_gt_i32_e64 s[70:71], 27, v230
	v_cmp_gt_i32_e64 s[66:67], 25, v230
	s_and_b64 s[68:69], s[70:71], s[68:69]
	v_cmp_gt_i32_e64 s[64:65], 24, v230
	s_and_b64 s[66:67], s[68:69], s[66:67]
	v_cmp_gt_i32_e64 s[62:63], 19, v230
	s_and_b64 s[64:65], s[66:67], s[64:65]
	v_cmp_gt_i32_e64 s[60:61], 18, v230
	s_and_b64 s[62:63], s[64:65], s[62:63]
	v_cmp_gt_i32_e64 s[58:59], 17, v230
	s_and_b64 s[60:61], s[62:63], s[60:61]
	v_cmp_gt_i32_e64 s[56:57], 16, v230
	s_and_b64 s[58:59], s[60:61], s[58:59]
	v_cmp_gt_i32_e64 s[54:55], 11, v230
	s_and_b64 s[56:57], s[58:59], s[56:57]
	v_cmp_gt_i32_e64 s[52:53], 10, v230
	s_and_b64 s[54:55], s[56:57], s[54:55]
	v_cmp_gt_i32_e64 s[50:51], 9, v230
	s_and_b64 s[52:53], s[54:55], s[52:53]
	v_cmp_gt_i32_e64 s[48:49], 8, v230
	s_and_b64 s[50:51], s[52:53], s[50:51]
	v_cmp_gt_i32_e64 s[46:47], 3, v230
	s_and_b64 s[48:49], s[50:51], s[48:49]
	v_cmp_gt_i32_e64 s[44:45], 2, v230
	s_and_b64 s[46:47], s[48:49], s[46:47]
	v_cmp_gt_i32_e64 s[42:43], 1, v230
	s_and_b64 s[44:45], s[46:47], s[44:45]
	v_cmp_gt_i32_e64 s[40:41], 0, v230
	s_and_b64 s[42:43], s[44:45], s[42:43]
	s_and_b64 s[40:41], s[42:43], s[40:41]
	v_cmp_gt_i32_e64 s[36:37], 58, v230
	v_cndmask_b32_e64 v102, v102, v213, s[40:41]
	v_cmp_gt_i32_e64 s[40:41], 59, v230
	v_cmp_gt_i32_e64 s[34:35], 57, v230
	s_and_b64 s[36:37], s[40:41], s[36:37]
	v_cmp_gt_i32_e64 s[30:31], 56, v230
	s_and_b64 s[34:35], s[36:37], s[34:35]
	v_cmp_gt_i32_e64 s[28:29], 51, v230
	s_and_b64 s[30:31], s[34:35], s[30:31]
	v_cmp_gt_i32_e64 s[26:27], 50, v230
	s_and_b64 s[28:29], s[30:31], s[28:29]
	v_cmp_gt_i32_e64 s[24:25], 49, v230
	s_and_b64 s[26:27], s[28:29], s[26:27]
	v_cmp_gt_i32_e64 s[22:23], 48, v230
	s_and_b64 s[24:25], s[26:27], s[24:25]
	v_cmp_gt_i32_e64 s[20:21], 43, v230
	s_and_b64 s[22:23], s[24:25], s[22:23]
	v_cmp_gt_i32_e64 s[18:19], 42, v230
	s_and_b64 s[20:21], s[22:23], s[20:21]
	v_cmp_gt_i32_e64 s[16:17], 41, v230
	s_and_b64 s[18:19], s[20:21], s[18:19]
	v_cmp_gt_i32_e64 s[14:15], 40, v230
	s_and_b64 s[16:17], s[18:19], s[16:17]
	v_cmp_gt_i32_e64 s[12:13], 35, v230
	s_and_b64 s[14:15], s[16:17], s[14:15]
	v_cmp_gt_i32_e64 s[10:11], 34, v230
	s_and_b64 s[12:13], s[14:15], s[12:13]
	v_cmp_gt_i32_e64 s[8:9], 33, v230
	s_and_b64 s[10:11], s[12:13], s[10:11]
	v_cmp_gt_i32_e32 vcc, 32, v230
	s_and_b64 s[8:9], s[10:11], s[8:9]
	s_and_b64 vcc, s[8:9], vcc
	v_cndmask_b32_e64 v117, v117, v213, s[70:71]
	v_cndmask_b32_e64 v116, v116, v213, s[68:69]
	v_cndmask_b32_e64 v115, v115, v213, s[66:67]
	v_cndmask_b32_e64 v114, v114, v213, s[64:65]
	v_cndmask_b32_e64 v113, v113, v213, s[62:63]
	v_cndmask_b32_e64 v112, v112, v213, s[60:61]
	v_cndmask_b32_e64 v111, v111, v213, s[58:59]
	v_cndmask_b32_e64 v110, v110, v213, s[56:57]
	v_cndmask_b32_e64 v109, v109, v213, s[54:55]
	v_cndmask_b32_e64 v108, v108, v213, s[52:53]
	v_cndmask_b32_e64 v107, v107, v213, s[50:51]
	v_cndmask_b32_e64 v106, v106, v213, s[48:49]
	v_cndmask_b32_e64 v105, v105, v213, s[46:47]
	v_cndmask_b32_e64 v104, v104, v213, s[44:45]
	v_cndmask_b32_e64 v103, v103, v213, s[42:43]
	v_cndmask_b32_e64 v101, v101, v213, s[40:41]
	v_cndmask_b32_e64 v100, v100, v213, s[36:37]
	v_cndmask_b32_e64 v99, v99, v213, s[34:35]
	v_cndmask_b32_e64 v98, v98, v213, s[30:31]
	v_cndmask_b32_e64 v97, v97, v213, s[28:29]
	v_cndmask_b32_e64 v96, v96, v213, s[26:27]
	v_cndmask_b32_e64 v95, v95, v213, s[24:25]
	v_cndmask_b32_e64 v94, v94, v213, s[22:23]
	v_cndmask_b32_e64 v93, v93, v213, s[20:21]
	v_cndmask_b32_e64 v92, v92, v213, s[18:19]
	v_cndmask_b32_e64 v91, v91, v213, s[16:17]
	v_cndmask_b32_e64 v90, v90, v213, s[14:15]
	v_cndmask_b32_e64 v89, v89, v213, s[12:13]
	v_cndmask_b32_e64 v88, v88, v213, s[10:11]
	v_cndmask_b32_e64 v87, v87, v213, s[8:9]
	v_cndmask_b32_e32 v86, v86, v213, vcc
.LBB0_1468:
	v_max_f32_e32 v82, v103, v103
	v_max_f32_e32 v83, v102, v102
	v_max_f32_e32 v82, v83, v82
	v_max3_f32 v82, v82, v104, v105
	v_max3_f32 v82, v82, v106, v107
	v_max3_f32 v82, v82, v108, v109
	v_max3_f32 v82, v82, v110, v111
	v_max3_f32 v82, v82, v112, v113
	v_max3_f32 v82, v82, v114, v115
	v_max3_f32 v82, v82, v116, v117
	v_max3_f32 v82, v82, v86, v87
	v_max3_f32 v82, v82, v88, v89
	v_max3_f32 v82, v82, v90, v91
	v_max3_f32 v82, v82, v92, v93
	v_max3_f32 v82, v82, v94, v95
	v_max3_f32 v82, v82, v96, v97
	v_max3_f32 v82, v82, v98, v99
	v_max3_f32 v82, v82, v100, v101
	v_mov_b32_e32 v83, v82
	s_nop 1
	v_permlane32_swap_b32_e32 v82, v83
	v_max_f32_e32 v83, v83, v83
	v_max_f32_e32 v82, v82, v82
	v_max_f32_e32 v82, v82, v83
	v_max_f32_e32 v84, v154, v154
	v_sub_f32_e32 v83, v82, v154
	v_max_f32_e32 v82, v84, v82
	v_sub_f32_e32 v84, v154, v82
	v_mul_f32_e32 v84, 0x3e0293ee, v84
	v_mul_f32_e32 v83, 0x3db504f3, v83
	v_exp_f32_e32 v84, v84
	v_cmp_ge_f32_e32 vcc, s84, v83
	s_cmp_eq_u64 vcc, exec
	s_cselect_b64 s[8:9], -1, 0
	s_waitcnt vmcnt(4) lgkmcnt(0)
	s_barrier
	s_waitcnt vmcnt(4)
	v_cndmask_b32_e64 v233, v84, 1.0, s[8:9]
	v_cmp_gt_f32_e32 vcc, 1.0, v233
	ds_write_b128 v211, v[4:7]
	ds_write_b128 v212, v[8:11]
	ds_write_b128 v214, v[12:15] offset:32768
	ds_write_b128 v214, v[150:153] offset:40960
	s_cbranch_vccz .LBB0_1472
	s_and_saveexec_b64 s[10:11], s[38:39]
	ds_write_b32 v217, v233 offset:128
	s_or_b64 exec, exec, s[10:11]
	s_waitcnt lgkmcnt(0)
	ds_read_b128 v[118:121], v216 offset:224
	ds_read_b128 v[122:125], v216 offset:192
	ds_read_b128 v[126:129], v216 offset:160
	ds_read_b128 v[130:133], v216 offset:128
	s_waitcnt lgkmcnt(3)
	v_pk_mul_f32 v[80:81], v[80:81], v[120:121]
	s_waitcnt lgkmcnt(2)
	v_pk_mul_f32 v[76:77], v[76:77], v[124:125]
	s_waitcnt lgkmcnt(1)
	v_pk_mul_f32 v[72:73], v[72:73], v[128:129]
	s_waitcnt lgkmcnt(0)
	v_pk_mul_f32 v[68:69], v[68:69], v[132:133]
	v_pk_mul_f32 v[78:79], v[78:79], v[118:119]
	v_pk_mul_f32 v[74:75], v[74:75], v[122:123]
	v_pk_mul_f32 v[70:71], v[70:71], v[126:127]
	v_pk_mul_f32 v[66:67], v[66:67], v[130:131]
	v_pk_mul_f32 v[64:65], v[64:65], v[120:121]
	v_pk_mul_f32 v[60:61], v[60:61], v[124:125]
	v_pk_mul_f32 v[56:57], v[56:57], v[128:129]
	v_pk_mul_f32 v[52:53], v[52:53], v[132:133]
	v_pk_mul_f32 v[62:63], v[62:63], v[118:119]
	v_pk_mul_f32 v[58:59], v[58:59], v[122:123]
	v_pk_mul_f32 v[54:55], v[54:55], v[126:127]
	v_pk_mul_f32 v[50:51], v[50:51], v[130:131]
	v_pk_mul_f32 v[48:49], v[48:49], v[120:121]
	v_pk_mul_f32 v[44:45], v[44:45], v[124:125]
	v_pk_mul_f32 v[40:41], v[40:41], v[128:129]
	v_pk_mul_f32 v[36:37], v[36:37], v[132:133]
	v_pk_mul_f32 v[46:47], v[46:47], v[118:119]
	v_pk_mul_f32 v[42:43], v[42:43], v[122:123]
	v_pk_mul_f32 v[38:39], v[38:39], v[126:127]
	v_pk_mul_f32 v[34:35], v[34:35], v[130:131]
	v_pk_mul_f32 v[32:33], v[32:33], v[120:121]
	v_pk_mul_f32 v[28:29], v[28:29], v[124:125]
	v_pk_mul_f32 v[24:25], v[24:25], v[128:129]
	v_pk_mul_f32 v[20:21], v[20:21], v[132:133]
	v_pk_mul_f32 v[30:31], v[30:31], v[118:119]
	v_pk_mul_f32 v[26:27], v[26:27], v[122:123]
	v_pk_mul_f32 v[22:23], v[22:23], v[126:127]
	v_pk_mul_f32 v[18:19], v[18:19], v[130:131]

; template <int VB>
; __device__ __forceinline__ void pv_tile(f32x16* o, int vb0, bf16x8 pa0, bf16x8 pa1, bf16x8 pa2, bf16x8 pa3) {
;     ...
;     PV_D0(0); PV_D0(1); PV_D0(2); PV_D0(3);
.LBB0_1475:
.LBB0_1476:
	s_add_u32 s100, s82, 0x258cc000
	s_addc_u32 s101, s83, 0
	v_lshl_add_u64 v[254:255], v[188:189], 0, s[100:101]
	global_load_dword v253, v[254:255], off
	v_lshl_add_u64 v[254:255], v[190:191], 0, s[100:101]
	global_load_dword v253, v[254:255], off
	s_add_u32 s100, s82, 0x258ca000
	s_addc_u32 s101, s83, 0
	v_lshl_add_u64 v[254:255], v[192:193], 0, s[100:101]
	global_load_dword v253, v[254:255], off
	v_lshl_add_u64 v[254:255], v[194:195], 0, s[100:101]
	global_load_dword v253, v[254:255], off
	ds_read_b64_tr_b16 v[196:197], v175 offset:0x4000
	ds_read_b64_tr_b16 v[198:199], v175 offset:0x4800
	ds_read_b64_tr_b16 v[200:201], v175 offset:0x5000
	ds_read_b64_tr_b16 v[202:203], v175 offset:0x5800
	ds_read_b64_tr_b16 v[238:239], v175 offset:0x6000
	ds_read_b64_tr_b16 v[240:241], v175 offset:0x6800
	ds_read_b64_tr_b16 v[242:243], v175 offset:0x7000
	ds_read_b64_tr_b16 v[244:245], v175 offset:0x7800
	s_waitcnt lgkmcnt(0)
	s_nop 0
	v_mfma_f32_32x32x16_bf16 v[66:81], v[154:157], v[196:199], v[66:81]
	ds_read_b64_tr_b16 v[196:197], v175 offset:0x4200
	ds_read_b64_tr_b16 v[198:199], v175 offset:0x4a00
	v_mfma_f32_32x32x16_bf16 v[66:81], v[158:161], v[200:203], v[66:81]
	ds_read_b64_tr_b16 v[200:201], v175 offset:0x5200
	ds_read_b64_tr_b16 v[202:203], v175 offset:0x5a00
	v_mfma_f32_32x32x16_bf16 v[66:81], v[162:165], v[238:241], v[66:81]
	ds_read_b64_tr_b16 v[238:239], v175 offset:0x6200
	ds_read_b64_tr_b16 v[240:241], v175 offset:0x6a00
	ds_read_b64_tr_b16 v[246:247], v175 offset:0x7200
	ds_read_b64_tr_b16 v[248:249], v175 offset:0x7a00
	s_waitcnt lgkmcnt(0)
	v_mfma_f32_32x32x16_bf16 v[66:81], v[166:169], v[242:245], v[66:81]
	v_mfma_f32_32x32x16_bf16 v[50:65], v[154:157], v[196:199], v[50:65]
	ds_read_b64_tr_b16 v[196:197], v175 offset:0x4400
	ds_read_b64_tr_b16 v[198:199], v175 offset:0x4c00
	v_mfma_f32_32x32x16_bf16 v[50:65], v[158:161], v[200:203], v[50:65]
	ds_read_b64_tr_b16 v[200:201], v175 offset:0x5400
	ds_read_b64_tr_b16 v[202:203], v175 offset:0x5c00
	v_mfma_f32_32x32x16_bf16 v[50:65], v[162:165], v[238:241], v[50:65]
	ds_read_b64_tr_b16 v[238:239], v175 offset:0x6400
	ds_read_b64_tr_b16 v[240:241], v175 offset:0x6c00
	ds_read_b64_tr_b16 v[242:243], v175 offset:0x7400
	ds_read_b64_tr_b16 v[244:245], v175 offset:0x7c00
	s_waitcnt lgkmcnt(0)
	v_mfma_f32_32x32x16_bf16 v[50:65], v[166:169], v[246:249], v[50:65]
	v_mfma_f32_32x32x16_bf16 v[34:49], v[154:157], v[196:199], v[34:49]
	ds_read_b64_tr_b16 v[196:197], v175 offset:0x4600
	ds_read_b64_tr_b16 v[198:199], v175 offset:0x4e00
	v_mfma_f32_32x32x16_bf16 v[34:49], v[158:161], v[200:203], v[34:49]
	ds_read_b64_tr_b16 v[200:201], v175 offset:0x5600
	ds_read_b64_tr_b16 v[202:203], v175 offset:0x5e00
	v_mfma_f32_32x32x16_bf16 v[34:49], v[162:165], v[238:241], v[34:49]
	ds_read_b64_tr_b16 v[238:239], v175 offset:0x6600
	ds_read_b64_tr_b16 v[240:241], v175 offset:0x6e00
	ds_read_b64_tr_b16 v[246:247], v175 offset:0x7600
	ds_read_b64_tr_b16 v[248:249], v175 offset:0x7e00
	s_waitcnt lgkmcnt(0)
	v_mfma_f32_32x32x16_bf16 v[34:49], v[166:169], v[242:245], v[34:49]
	v_mfma_f32_32x32x16_bf16 v[18:33], v[154:157], v[196:199], v[18:33]
	s_add_i32 s6, s74, 64
	s_cmp_le_i32 s6, s73
	v_mfma_f32_32x32x16_bf16 v[18:33], v[158:161], v[200:203], v[18:33]
	v_mfma_f32_32x32x16_bf16 v[18:33], v[162:165], v[238:241], v[18:33]
	v_mfma_f32_32x32x16_bf16 v[18:33], v[166:169], v[246:249], v[18:33]
	s_cbranch_scc1 .LBB0_1478
; __device__ __forceinline__ void mask_tile(f32x16& p0, f32x16& p1, int dq) {
;     const float NEG = -__builtin_inff();
; #pragma unroll
;     for (int r = 0; r < 16; ++r) {
;         const int c = (r & 3) + 8 * (r >> 2);
;         if (dq - c < 0) p0[r] = NEG;
;         if (dq - c - 32 < 0) p1[r] = NEG;
;     }
; }
; __device__ __forceinline__ void partialSM(f32x16& p0, f32x16& p1, float& m_reg, float& mn, float& alpha) {
;     float pmax = p0[0];
; #pragma unroll
;     for (int r = 1; r < 16; ++r) pmax = fmaxf(pmax, p0[r]);
; #pragma unroll
;     for (int r = 0; r < 16; ++r) pmax = fmaxf(pmax, p1[r]);
;     { auto rr = __builtin_amdgcn_permlane32_swap(__float_as_uint(pmax), __float_as_uint(pmax), false, false);
;       pmax = fmaxf(__uint_as_float(rr[0]), __uint_as_float(rr[1])); }
;     if (__builtin_expect(__all((pmax - m_reg) * SCALE <= THR), 1)) { mn = m_reg; alpha = 1.f; }
;     else { mn = fmaxf(m_reg, pmax); alpha = __builtin_amdgcn_exp2f((m_reg - mn) * C2); m_reg = mn; }
	v_subrev_u32_e32 v154, 64, v230
	v_cmp_gt_i32_e64 s[66:67], 26, v154
	v_cmp_gt_i32_e64 s[68:69], 27, v154
	v_cmp_gt_i32_e64 s[64:65], 25, v154
	s_and_b64 s[66:67], s[68:69], s[66:67]
	v_cmp_gt_i32_e64 s[62:63], 24, v154
	s_and_b64 s[64:65], s[66:67], s[64:65]
	v_cmp_gt_i32_e64 s[60:61], 19, v154
	s_and_b64 s[62:63], s[64:65], s[62:63]
	v_cmp_gt_i32_e64 s[58:59], 18, v154
	s_and_b64 s[60:61], s[62:63], s[60:61]
	v_cmp_gt_i32_e64 s[56:57], 17, v154
	s_and_b64 s[58:59], s[60:61], s[58:59]
	v_cmp_gt_i32_e64 s[54:55], 16, v154
	s_and_b64 s[56:57], s[58:59], s[56:57]
	v_cmp_gt_i32_e64 s[52:53], 11, v154
	s_and_b64 s[54:55], s[56:57], s[54:55]
	v_cmp_gt_i32_e64 s[50:51], 10, v154
	s_and_b64 s[52:53], s[54:55], s[52:53]
	v_cmp_gt_i32_e64 s[48:49], 9, v154
	s_and_b64 s[50:51], s[52:53], s[50:51]
	v_cmp_gt_i32_e64 s[46:47], 8, v154
	s_and_b64 s[48:49], s[50:51], s[48:49]
	v_cmp_gt_i32_e64 s[44:45], 3, v154
	s_and_b64 s[46:47], s[48:49], s[46:47]
	v_cmp_gt_i32_e64 s[42:43], 2, v154
	s_and_b64 s[44:45], s[46:47], s[44:45]
	v_cmp_gt_i32_e64 s[40:41], 1, v154
	s_and_b64 s[42:43], s[44:45], s[42:43]
	v_cmp_gt_i32_e64 s[36:37], 0, v154
	s_and_b64 s[40:41], s[42:43], s[40:41]
	s_and_b64 s[36:37], s[40:41], s[36:37]
	v_cmp_gt_i32_e64 s[34:35], 58, v154
	v_cndmask_b32_e64 v130, v130, v213, s[36:37]
	v_cmp_gt_i32_e64 s[36:37], 59, v154
	v_cmp_gt_i32_e64 s[30:31], 57, v154
	s_and_b64 s[34:35], s[36:37], s[34:35]
	v_cmp_gt_i32_e64 s[28:29], 56, v154
	s_and_b64 s[30:31], s[34:35], s[30:31]
	v_cmp_gt_i32_e64 s[26:27], 51, v154
	s_and_b64 s[28:29], s[30:31], s[28:29]
	v_cmp_gt_i32_e64 s[24:25], 50, v154
	s_and_b64 s[26:27], s[28:29], s[26:27]
	v_cmp_gt_i32_e64 s[22:23], 49, v154
	s_and_b64 s[24:25], s[26:27], s[24:25]
	v_cmp_gt_i32_e64 s[20:21], 48, v154
	s_and_b64 s[22:23], s[24:25], s[22:23]
	v_cmp_gt_i32_e64 s[18:19], 43, v154
	s_and_b64 s[20:21], s[22:23], s[20:21]
	v_cmp_gt_i32_e64 s[16:17], 42, v154
	s_and_b64 s[18:19], s[20:21], s[18:19]
	v_cmp_gt_i32_e64 s[14:15], 41, v154
	s_and_b64 s[16:17], s[18:19], s[16:17]
	v_cmp_gt_i32_e64 s[12:13], 40, v154
	s_and_b64 s[14:15], s[16:17], s[14:15]
	v_cmp_gt_i32_e64 s[10:11], 35, v154
	s_and_b64 s[12:13], s[14:15], s[12:13]
	v_cmp_gt_i32_e64 s[8:9], 34, v154
	s_and_b64 s[10:11], s[12:13], s[10:11]
	v_cmp_gt_i32_e64 s[6:7], 33, v154
	s_and_b64 s[8:9], s[10:11], s[8:9]
	v_cmp_gt_i32_e32 vcc, 32, v154
	s_and_b64 s[6:7], s[8:9], s[6:7]
	s_and_b64 vcc, s[6:7], vcc
	v_cndmask_b32_e64 v145, v145, v213, s[68:69]
	v_cndmask_b32_e64 v144, v144, v213, s[66:67]
	v_cndmask_b32_e64 v143, v143, v213, s[64:65]
	v_cndmask_b32_e64 v142, v142, v213, s[62:63]
	v_cndmask_b32_e64 v141, v141, v213, s[60:61]
	v_cndmask_b32_e64 v140, v140, v213, s[58:59]
	v_cndmask_b32_e64 v139, v139, v213, s[56:57]
	v_cndmask_b32_e64 v138, v138, v213, s[54:55]
	v_cndmask_b32_e64 v137, v137, v213, s[52:53]
	v_cndmask_b32_e64 v136, v136, v213, s[50:51]
	v_cndmask_b32_e64 v135, v135, v213, s[48:49]
	v_cndmask_b32_e64 v134, v134, v213, s[46:47]
	v_cndmask_b32_e64 v133, v133, v213, s[44:45]
	v_cndmask_b32_e64 v132, v132, v213, s[42:43]
	v_cndmask_b32_e64 v131, v131, v213, s[40:41]
	v_cndmask_b32_e64 v129, v129, v213, s[36:37]
	v_cndmask_b32_e64 v128, v128, v213, s[34:35]
	v_cndmask_b32_e64 v127, v127, v213, s[30:31]
	v_cndmask_b32_e64 v126, v126, v213, s[28:29]
	v_cndmask_b32_e64 v125, v125, v213, s[26:27]
	v_cndmask_b32_e64 v124, v124, v213, s[24:25]
	v_cndmask_b32_e64 v123, v123, v213, s[22:23]
	v_cndmask_b32_e64 v122, v122, v213, s[20:21]
	v_cndmask_b32_e64 v121, v121, v213, s[18:19]
	v_cndmask_b32_e64 v120, v120, v213, s[16:17]
	v_cndmask_b32_e64 v119, v119, v213, s[14:15]
	v_cndmask_b32_e64 v118, v118, v213, s[12:13]
	v_cndmask_b32_e64 v117, v117, v213, s[10:11]
	v_cndmask_b32_e64 v116, v116, v213, s[8:9]
	v_cndmask_b32_e64 v115, v115, v213, s[6:7]
	v_cndmask_b32_e32 v114, v114, v213, vcc
.LBB0_1478:
	v_max_f32_e32 v154, v131, v131
	v_max_f32_e32 v155, v130, v130
	v_max_f32_e32 v154, v155, v154
	v_max3_f32 v154, v154, v132, v133
	v_max3_f32 v154, v154, v134, v135
	v_max3_f32 v154, v154, v136, v137
	v_max3_f32 v154, v154, v138, v139
	v_max3_f32 v154, v154, v140, v141
	v_max3_f32 v154, v154, v142, v143
	v_max3_f32 v154, v154, v144, v145
	v_max3_f32 v154, v154, v114, v115
	v_max3_f32 v154, v154, v116, v117
	v_max3_f32 v154, v154, v118, v119
	v_max3_f32 v154, v154, v120, v121
	v_max3_f32 v154, v154, v122, v123
	v_max3_f32 v154, v154, v124, v125
	v_max3_f32 v154, v154, v126, v127
	v_max3_f32 v154, v154, v128, v129
	v_mov_b32_e32 v155, v154
	s_nop 1
	v_permlane32_swap_b32_e32 v154, v155
	v_max_f32_e32 v155, v155, v155
	v_max_f32_e32 v154, v154, v154
	v_max_f32_e32 v154, v154, v155
	v_sub_f32_e32 v155, v154, v234
	v_mul_f32_e32 v155, 0x3db504f3, v155
	v_cmp_ge_f32_e32 vcc, s84, v155
	s_cmp_eq_u64 vcc, exec
	s_cselect_b64 s[6:7], -1, 0
	s_andn2_b64 vcc, exec, s[70:71]
	s_waitcnt vmcnt(4) lgkmcnt(0)
	s_barrier
	s_cbranch_vccnz .LBB0_1480
	s_waitcnt vmcnt(4)
	ds_write_b128 v211, v[4:7] offset:16384
	ds_write_b128 v212, v[8:11] offset:16384
	ds_write_b128 v214, v[12:15] offset:49152
	ds_write_b128 v214, v[150:153] offset:57344
